# peeled first K-iteration with inline-zero accumulator input in the in-projection and gate/up GEMM loops (no accumulator zeroing moves), on top of the 2-chunk attention schedule
# baseline (speedup 1.0000x reference)
; #define PG8_STAGE(bufoff, gbase, voff) do { _Pragma("unroll") for (int _i = 0; _i < 2; ++_i) \
;         __builtin_amdgcn_global_load_lds((const unsigned*)((const char*)(gbase) + (voff)[_i]), (PG8_LAS unsigned*)(lds + (bufoff) + ldsw + _i * 8192), 16, 0, 0); } while (0)
; #define PG8_LDA(dst, b, h) do { _Pragma("unroll") for (int m = 0; m < 4; ++m) _Pragma("unroll") for (int k = 0; k < 2; ++k) dst[m][k] = *(const PG8_LAS bf16x8*)(lds + PG8_SA(b, h) + aoff + m * 2048 + k * 1024); } while (0)
; #define PG8_LDB(dst, b, h) do { _Pragma("unroll") for (int n = 0; n < 2; ++n) _Pragma("unroll") for (int k = 0; k < 2; ++k) dst[n][k] = *(const PG8_LAS bf16x8*)(lds + PG8_SB(b, h) + boff + n * 2048 + k * 1024); } while (0)
; #define PG8_WAIT_V(n) asm volatile("s_waitcnt vmcnt(" #n ")" ::: "memory")
; #define PG8_WAIT_L(n) asm volatile("s_waitcnt lgkmcnt(" #n ")" ::: "memory")
; #define PG8_BAR __builtin_amdgcn_s_barrier()
; #define PG8_SCHED __builtin_amdgcn_sched_barrier(0)
; template <class Epi, class Sched, bool ALIGN_EPI = false, bool SP2 = false>
; __device__ __forceinline__ void gemm_phase(PG8_LAS unsigned char* lds, const Gemm g, const Sched& S, const Epi& E) {
;     ...
;         const bool has_next = S.next(ui + 1, nxt);
;         const char* nA = has_next ? (const char*)g.A + (size_t)nxt.pm * tstep : cA; const char* nB = has_next ? (const char*)g.Bt + (size_t)nxt.pn * tstep : cB;
;         for (int t = 0; t < nt; t += 2) {
;             const bool last = (t == nt - 2);
;             const char* a1 = cA + (size_t)(t + 1) * kstep;
;             const char* a2 = last ? nA : cA + (size_t)(t + 2) * kstep; const char* b2 = last ? nB : cB + (size_t)(t + 2) * kstep;
;             const char* a3 = a2 + kstep; const char* b3 = b2 + kstep;
;             if (last && has_next) S.a_ready(nxt);
;             if constexpr (SP2) {
;             PG8_LDB(B0, 0, 0); PG8_LDB(B1, 0, 1); PG8_SCHED; PG8_LDA(At, 0, 0); PG8_STAGE(PG8_SA(1, 1), a1 + hstep, voffA);
;             PG8_WAIT_V(8); PG8_WAIT_L(0); PG8_BAR; PG8_MMA(0, 0, At, B0); PG8_MMA(0, 1, At, B1); PG8_BAR; PG8_SCHED;
;             PG8_LDA(At, 0, 1); PG8_STAGE(PG8_SB(0, 0), b2, voffB); PG8_STAGE(PG8_SB(0, 1), b2 + hstep, voffB); PG8_STAGE(PG8_SA(0, 0), a2, voffA);
;             PG8_WAIT_V(8); PG8_WAIT_L(0); PG8_BAR; PG8_MMA(1, 0, At, B0); PG8_MMA(1, 1, At, B1); PG8_BAR; PG8_SCHED;
.LBB0_140:
	s_ashr_i32 s75, s74, 31
	s_lshl_b64 s[30:31], s[74:75], 19
	s_add_u32 s76, s20, s30
	s_addc_u32 s77, s21, s31
	s_and_b64 s[30:31], s[4:5], exec
	s_cselect_b32 s7, s77, s85
	s_cselect_b32 s9, s76, s84
	s_ashr_i32 s73, s72, 31
	s_lshl_b64 s[30:31], s[72:73], 19
	s_add_u32 s78, s89, s30
	s_addc_u32 s79, s90, s31
	s_and_b64 s[30:31], s[4:5], exec
	s_cselect_b32 s10, s79, s87
	s_cselect_b32 s69, s78, s86
	s_add_u32 s84, s84, 0x40080
	s_addc_u32 s85, s85, 0
	s_add_u32 s73, s86, 0x100
	s_addc_u32 s75, s87, 0
	s_mov_b32 vcc_lo, -2
	ds_read_b128 v[130:133], v196
	ds_read_b128 v[134:137], v196 offset:1024
	ds_read_b128 v[138:141], v196 offset:2048
	ds_read_b128 v[142:145], v196 offset:3072
	s_waitcnt lgkmcnt(0)
	ds_read_b128 v[170:173], v197
	ds_read_b128 v[174:177], v197 offset:1024
	ds_read_b128 v[178:181], v197 offset:2048
	ds_read_b128 v[182:185], v197 offset:3072
	s_add_u32 s18, s84, 0xfffc0080
	s_addc_u32 s19, s85, -1
	s_cmp_eq_u32 vcc_lo, 12
	s_cselect_b32 s87, s7, s19
	s_cselect_b32 s86, s9, s18
	s_cselect_b32 s31, s10, s75
	s_cselect_b32 s30, s69, s73
	v_lshl_add_u64 v[190:191], s[84:85], 0, v[162:163]
	s_add_i32 m0, s91, 0xc000
	ds_read_b128 v[186:189], v198
	ds_read_b128 v[202:205], v198 offset:1024
	ds_read_b128 v[208:211], v198 offset:2048
	ds_read_b128 v[212:215], v198 offset:3072
	ds_read_b128 v[216:219], v198 offset:4096
	ds_read_b128 v[220:223], v198 offset:5120
	ds_read_b128 v[224:227], v198 offset:6144
	ds_read_b128 v[228:231], v198 offset:7168
	global_load_lds_dwordx4 v[190:191], off
	v_lshl_add_u64 v[190:191], s[84:85], 0, v[164:165]
	s_add_i32 m0, s91, 0xe000
	s_nop 0
	global_load_lds_dwordx4 v[190:191], off
	s_waitcnt vmcnt(8)
	s_waitcnt lgkmcnt(0)
	s_barrier
	s_setprio 1
	s_waitcnt lgkmcnt(0)
	v_mfma_f32_16x16x32_bf16 v[126:129], v[130:133], v[186:189], 0
	v_mfma_f32_16x16x32_bf16 v[122:125], v[138:141], v[186:189], 0
	v_mfma_f32_16x16x32_bf16 v[110:113], v[130:133], v[208:211], 0
	v_mfma_f32_16x16x32_bf16 v[106:109], v[138:141], v[208:211], 0
	v_mfma_f32_16x16x32_bf16 v[94:97], v[130:133], v[216:219], 0
	v_mfma_f32_16x16x32_bf16 v[90:93], v[138:141], v[216:219], 0
	v_mfma_f32_16x16x32_bf16 v[78:81], v[130:133], v[224:227], 0
	v_mfma_f32_16x16x32_bf16 v[74:77], v[138:141], v[224:227], 0
	v_mfma_f32_16x16x32_bf16 v[126:129], v[134:137], v[202:205], v[126:129]
	v_mfma_f32_16x16x32_bf16 v[122:125], v[142:145], v[202:205], v[122:125]
	v_mfma_f32_16x16x32_bf16 v[110:113], v[134:137], v[212:215], v[110:113]
	v_mfma_f32_16x16x32_bf16 v[106:109], v[142:145], v[212:215], v[106:109]
	v_mfma_f32_16x16x32_bf16 v[94:97], v[134:137], v[220:223], v[94:97]
	v_mfma_f32_16x16x32_bf16 v[90:93], v[142:145], v[220:223], v[90:93]
	v_mfma_f32_16x16x32_bf16 v[78:81], v[134:137], v[228:231], v[78:81]
	v_mfma_f32_16x16x32_bf16 v[74:77], v[142:145], v[228:231], v[74:77]
	s_setprio 0
	s_setprio 1
	v_mfma_f32_16x16x32_bf16 v[118:121], v[170:173], v[186:189], 0
	v_mfma_f32_16x16x32_bf16 v[114:117], v[178:181], v[186:189], 0
	v_mfma_f32_16x16x32_bf16 v[102:105], v[170:173], v[208:211], 0
	v_mfma_f32_16x16x32_bf16 v[98:101], v[178:181], v[208:211], 0
	v_mfma_f32_16x16x32_bf16 v[86:89], v[170:173], v[216:219], 0
	v_mfma_f32_16x16x32_bf16 v[82:85], v[178:181], v[216:219], 0
	v_mfma_f32_16x16x32_bf16 v[70:73], v[170:173], v[224:227], 0
	v_mfma_f32_16x16x32_bf16 v[66:69], v[178:181], v[224:227], 0
	v_mfma_f32_16x16x32_bf16 v[118:121], v[174:177], v[202:205], v[118:121]
	v_mfma_f32_16x16x32_bf16 v[114:117], v[182:185], v[202:205], v[114:117]
	v_mfma_f32_16x16x32_bf16 v[102:105], v[174:177], v[212:215], v[102:105]
	v_mfma_f32_16x16x32_bf16 v[98:101], v[182:185], v[212:215], v[98:101]
	v_mfma_f32_16x16x32_bf16 v[86:89], v[174:177], v[220:223], v[86:89]
	v_mfma_f32_16x16x32_bf16 v[82:85], v[182:185], v[220:223], v[82:85]
	v_mfma_f32_16x16x32_bf16 v[70:73], v[174:177], v[228:231], v[70:73]
	v_mfma_f32_16x16x32_bf16 v[66:69], v[182:185], v[228:231], v[66:69]
	s_setprio 0
	s_barrier
	s_add_i32 s18, s58, s88
	v_lshl_add_u64 v[190:191], s[30:31], 0, v[148:149]
	s_mov_b32 m0, s18
	ds_read_b128 v[186:189], v198 offset:16384
	ds_read_b128 v[202:205], v198 offset:17408
	ds_read_b128 v[208:211], v198 offset:18432
	ds_read_b128 v[212:215], v198 offset:19456
	ds_read_b128 v[216:219], v198 offset:20480
	ds_read_b128 v[220:223], v198 offset:21504
	ds_read_b128 v[224:227], v198 offset:22528
	ds_read_b128 v[228:231], v198 offset:23552
	global_load_lds_dwordx4 v[190:191], off
	s_add_i32 m0, s18, 0x2000
	s_add_u32 s18, s30, 0x40000
	v_lshl_add_u64 v[232:233], s[30:31], 0, v[152:153]
	s_addc_u32 s19, s31, 0
	s_add_i32 vcc_hi, s59, s88
	global_load_lds_dwordx4 v[232:233], off
	v_lshl_add_u64 v[234:235], s[18:19], 0, v[148:149]
	s_mov_b32 m0, vcc_hi
	v_lshl_add_u64 v[238:239], s[86:87], 0, v[150:151]
	global_load_lds_dwordx4 v[234:235], off
	v_lshl_add_u64 v[234:235], s[18:19], 0, v[152:153]
	s_add_i32 m0, vcc_hi, 0x2000
	s_nop 0
	global_load_lds_dwordx4 v[234:235], off
	v_lshl_add_u64 v[234:235], s[86:87], 0, v[146:147]
	s_mov_b32 m0, s91
	s_nop 0
	global_load_lds_dwordx4 v[234:235], off
	s_mov_b32 m0, s92
	s_nop 0
	global_load_lds_dwordx4 v[238:239], off
	s_waitcnt vmcnt(8)
	s_waitcnt lgkmcnt(0)
	s_barrier
; #define PG8_STAGE(bufoff, gbase, voff) do { _Pragma("unroll") for (int _i = 0; _i < 2; ++_i) \
;         __builtin_amdgcn_global_load_lds((const unsigned*)((const char*)(gbase) + (voff)[_i]), (PG8_LAS unsigned*)(lds + (bufoff) + ldsw + _i * 8192), 16, 0, 0); } while (0)
; #define PG8_LDA(dst, b, h) do { _Pragma("unroll") for (int m = 0; m < 4; ++m) _Pragma("unroll") for (int k = 0; k < 2; ++k) dst[m][k] = *(const PG8_LAS bf16x8*)(lds + PG8_SA(b, h) + aoff + m * 2048 + k * 1024); } while (0)
; #define PG8_LDB(dst, b, h) do { _Pragma("unroll") for (int n = 0; n < 2; ++n) _Pragma("unroll") for (int k = 0; k < 2; ++k) dst[n][k] = *(const PG8_LAS bf16x8*)(lds + PG8_SB(b, h) + boff + n * 2048 + k * 1024); } while (0)
; #define PG8_MMA(ai, bj, At, Bt) do { __builtin_amdgcn_s_setprio(1); _Pragma("unroll") for (int m = 0; m < 4; ++m) _Pragma("unroll") for (int n = 0; n < 2; ++n) _Pragma("unroll") for (int k = 0; k < 2; ++k) \
;         acc[ai][bj][m][n] = __builtin_amdgcn_mfma_f32_16x16x32_bf16(Bt[n][k], At[m][k], acc[ai][bj][m][n], 0, 0, 0); __builtin_amdgcn_s_setprio(0); } while (0)
; #define PG8_WAIT_V(n) asm volatile("s_waitcnt vmcnt(" #n ")" ::: "memory")
; #define PG8_WAIT_L(n) asm volatile("s_waitcnt lgkmcnt(" #n ")" ::: "memory")
; #define PG8_BAR __builtin_amdgcn_s_barrier()
; #define PG8_SCHED __builtin_amdgcn_sched_barrier(0)
; template <class Epi, class Sched, bool ALIGN_EPI = false, bool SP2 = false>
; __device__ __forceinline__ void gemm_phase(PG8_LAS unsigned char* lds, const Gemm g, const Sched& S, const Epi& E) {
;     ...
;             PG8_WAIT_V(8); PG8_WAIT_L(0); PG8_BAR; PG8_MMA(1, 0, At, B0); PG8_MMA(1, 1, At, B1); PG8_BAR; PG8_SCHED;
;             PG8_LDB(B0, 1, 0); PG8_LDB(B1, 1, 1); PG8_SCHED; PG8_LDA(At, 1, 0); PG8_STAGE(PG8_SA(0, 1), a2 + hstep, voffA);
;             PG8_WAIT_V(8); PG8_WAIT_L(0); PG8_BAR; PG8_MMA(0, 0, At, B0); PG8_MMA(0, 1, At, B1); PG8_BAR; PG8_SCHED;
	s_setprio 1
	s_waitcnt lgkmcnt(0)
	v_mfma_f32_16x16x32_bf16 v[62:65], v[130:133], v[186:189], 0
	v_mfma_f32_16x16x32_bf16 v[58:61], v[138:141], v[186:189], 0
	v_mfma_f32_16x16x32_bf16 v[46:49], v[130:133], v[208:211], 0
	v_mfma_f32_16x16x32_bf16 v[42:45], v[138:141], v[208:211], 0
	v_mfma_f32_16x16x32_bf16 v[30:33], v[130:133], v[216:219], 0
	v_mfma_f32_16x16x32_bf16 v[26:29], v[138:141], v[216:219], 0
	v_mfma_f32_16x16x32_bf16 v[14:17], v[130:133], v[224:227], 0
	v_mfma_f32_16x16x32_bf16 v[10:13], v[138:141], v[224:227], 0
	v_mfma_f32_16x16x32_bf16 v[62:65], v[134:137], v[202:205], v[62:65]
	v_mfma_f32_16x16x32_bf16 v[58:61], v[142:145], v[202:205], v[58:61]
	v_mfma_f32_16x16x32_bf16 v[46:49], v[134:137], v[212:215], v[46:49]
	v_mfma_f32_16x16x32_bf16 v[42:45], v[142:145], v[212:215], v[42:45]
	v_mfma_f32_16x16x32_bf16 v[30:33], v[134:137], v[220:223], v[30:33]
	v_mfma_f32_16x16x32_bf16 v[26:29], v[142:145], v[220:223], v[26:29]
	v_mfma_f32_16x16x32_bf16 v[14:17], v[134:137], v[228:231], v[14:17]
	v_mfma_f32_16x16x32_bf16 v[10:13], v[142:145], v[228:231], v[10:13]
	s_setprio 0
	s_setprio 1
	v_mfma_f32_16x16x32_bf16 v[54:57], v[170:173], v[186:189], 0
	v_mfma_f32_16x16x32_bf16 v[50:53], v[178:181], v[186:189], 0
	v_mfma_f32_16x16x32_bf16 v[38:41], v[170:173], v[208:211], 0
	v_mfma_f32_16x16x32_bf16 v[34:37], v[178:181], v[208:211], 0
	v_mfma_f32_16x16x32_bf16 v[22:25], v[170:173], v[216:219], 0
	v_mfma_f32_16x16x32_bf16 v[18:21], v[178:181], v[216:219], 0
	v_mfma_f32_16x16x32_bf16 v[6:9], v[170:173], v[224:227], 0
	v_mfma_f32_16x16x32_bf16 v[2:5], v[178:181], v[224:227], 0
	v_mfma_f32_16x16x32_bf16 v[54:57], v[174:177], v[202:205], v[54:57]
	v_mfma_f32_16x16x32_bf16 v[50:53], v[182:185], v[202:205], v[50:53]
	v_mfma_f32_16x16x32_bf16 v[38:41], v[174:177], v[212:215], v[38:41]
	v_mfma_f32_16x16x32_bf16 v[34:37], v[182:185], v[212:215], v[34:37]
	v_mfma_f32_16x16x32_bf16 v[22:25], v[174:177], v[220:223], v[22:25]
	v_mfma_f32_16x16x32_bf16 v[18:21], v[182:185], v[220:223], v[18:21]
	v_mfma_f32_16x16x32_bf16 v[6:9], v[174:177], v[228:231], v[6:9]
	v_mfma_f32_16x16x32_bf16 v[2:5], v[182:185], v[228:231], v[2:5]
	s_setprio 0
	s_barrier
	s_add_i32 vcc_hi, 0, 0x18000
	s_add_i32 s52, 0, 0x1c000
	v_add_u32_e32 v142, vcc_hi, v157
	v_add_u32_e32 v154, s52, v157
	ds_read_b128 v[130:133], v142
	ds_read_b128 v[134:137], v142 offset:1024
	ds_read_b128 v[138:141], v142 offset:2048
	ds_read_b128 v[142:145], v142 offset:3072
	ds_read_b128 v[170:173], v154
	ds_read_b128 v[174:177], v154 offset:1024
	ds_read_b128 v[178:181], v154 offset:2048
	ds_read_b128 v[182:185], v154 offset:3072
	s_add_u32 s18, s86, 0x40000
	s_addc_u32 s19, s87, 0
	s_mov_b32 m0, s93
	v_lshl_add_u64 v[240:241], s[18:19], 0, v[146:147]
	ds_read_b128 v[186:189], v198 offset:32768
	ds_read_b128 v[202:205], v198 offset:33792
	ds_read_b128 v[208:211], v198 offset:34816
	ds_read_b128 v[212:215], v198 offset:35840
	ds_read_b128 v[216:219], v198 offset:36864
	ds_read_b128 v[220:223], v198 offset:37888
	ds_read_b128 v[224:227], v198 offset:38912
	ds_read_b128 v[228:231], v198 offset:39936
	global_load_lds_dwordx4 v[240:241], off
	v_lshl_add_u64 v[240:241], s[18:19], 0, v[150:151]
	s_mov_b32 m0, s95
	s_nop 0
	global_load_lds_dwordx4 v[240:241], off
	s_waitcnt vmcnt(8)
	s_waitcnt lgkmcnt(0)
	s_barrier
	s_setprio 1
	s_waitcnt lgkmcnt(0)
	v_mfma_f32_16x16x32_bf16 v[126:129], v[130:133], v[186:189], v[126:129]
	v_mfma_f32_16x16x32_bf16 v[122:125], v[138:141], v[186:189], v[122:125]
	v_mfma_f32_16x16x32_bf16 v[110:113], v[130:133], v[208:211], v[110:113]
	v_mfma_f32_16x16x32_bf16 v[106:109], v[138:141], v[208:211], v[106:109]
	v_mfma_f32_16x16x32_bf16 v[94:97], v[130:133], v[216:219], v[94:97]
	v_mfma_f32_16x16x32_bf16 v[90:93], v[138:141], v[216:219], v[90:93]
	v_mfma_f32_16x16x32_bf16 v[78:81], v[130:133], v[224:227], v[78:81]
	v_mfma_f32_16x16x32_bf16 v[74:77], v[138:141], v[224:227], v[74:77]
	v_mfma_f32_16x16x32_bf16 v[126:129], v[134:137], v[202:205], v[126:129]
	v_mfma_f32_16x16x32_bf16 v[122:125], v[142:145], v[202:205], v[122:125]
	v_mfma_f32_16x16x32_bf16 v[110:113], v[134:137], v[212:215], v[110:113]
	v_mfma_f32_16x16x32_bf16 v[106:109], v[142:145], v[212:215], v[106:109]
	v_mfma_f32_16x16x32_bf16 v[94:97], v[134:137], v[220:223], v[94:97]
	v_mfma_f32_16x16x32_bf16 v[90:93], v[142:145], v[220:223], v[90:93]
	v_mfma_f32_16x16x32_bf16 v[78:81], v[134:137], v[228:231], v[78:81]
	v_mfma_f32_16x16x32_bf16 v[74:77], v[142:145], v[228:231], v[74:77]
	s_setprio 0
	s_setprio 1
	v_mfma_f32_16x16x32_bf16 v[118:121], v[170:173], v[186:189], v[118:121]
	v_mfma_f32_16x16x32_bf16 v[114:117], v[178:181], v[186:189], v[114:117]
	v_mfma_f32_16x16x32_bf16 v[102:105], v[170:173], v[208:211], v[102:105]
	v_mfma_f32_16x16x32_bf16 v[98:101], v[178:181], v[208:211], v[98:101]
	v_mfma_f32_16x16x32_bf16 v[86:89], v[170:173], v[216:219], v[86:89]
	v_mfma_f32_16x16x32_bf16 v[82:85], v[178:181], v[216:219], v[82:85]
	v_mfma_f32_16x16x32_bf16 v[70:73], v[170:173], v[224:227], v[70:73]
	v_mfma_f32_16x16x32_bf16 v[66:69], v[178:181], v[224:227], v[66:69]
	v_mfma_f32_16x16x32_bf16 v[118:121], v[174:177], v[202:205], v[118:121]
	v_mfma_f32_16x16x32_bf16 v[114:117], v[182:185], v[202:205], v[114:117]
	v_mfma_f32_16x16x32_bf16 v[102:105], v[174:177], v[212:215], v[102:105]
	v_mfma_f32_16x16x32_bf16 v[98:101], v[182:185], v[212:215], v[98:101]
	v_mfma_f32_16x16x32_bf16 v[86:89], v[174:177], v[220:223], v[86:89]
	v_mfma_f32_16x16x32_bf16 v[82:85], v[182:185], v[220:223], v[82:85]
	v_mfma_f32_16x16x32_bf16 v[70:73], v[174:177], v[228:231], v[70:73]
	v_mfma_f32_16x16x32_bf16 v[66:69], v[182:185], v[228:231], v[66:69]
	s_setprio 0
	s_barrier
; #define PG8_STAGE(bufoff, gbase, voff) do { _Pragma("unroll") for (int _i = 0; _i < 2; ++_i) \
;         __builtin_amdgcn_global_load_lds((const unsigned*)((const char*)(gbase) + (voff)[_i]), (PG8_LAS unsigned*)(lds + (bufoff) + ldsw + _i * 8192), 16, 0, 0); } while (0)
; #define PG8_LDA(dst, b, h) do { _Pragma("unroll") for (int m = 0; m < 4; ++m) _Pragma("unroll") for (int k = 0; k < 2; ++k) dst[m][k] = *(const PG8_LAS bf16x8*)(lds + PG8_SA(b, h) + aoff + m * 2048 + k * 1024); } while (0)
; #define PG8_MMA(ai, bj, At, Bt) do { __builtin_amdgcn_s_setprio(1); _Pragma("unroll") for (int m = 0; m < 4; ++m) _Pragma("unroll") for (int n = 0; n < 2; ++n) _Pragma("unroll") for (int k = 0; k < 2; ++k) \
;         acc[ai][bj][m][n] = __builtin_amdgcn_mfma_f32_16x16x32_bf16(Bt[n][k], At[m][k], acc[ai][bj][m][n], 0, 0, 0); __builtin_amdgcn_s_setprio(0); } while (0)
; #define PG8_WAIT_V(n) asm volatile("s_waitcnt vmcnt(" #n ")" ::: "memory")
; #define PG8_WAIT_L(n) asm volatile("s_waitcnt lgkmcnt(" #n ")" ::: "memory")
; #define PG8_BAR __builtin_amdgcn_s_barrier()
; #define PG8_SCHED __builtin_amdgcn_sched_barrier(0)
; template <class Epi, class Sched, bool ALIGN_EPI = false, bool SP2 = false>
; __device__ __forceinline__ void gemm_phase(PG8_LAS unsigned char* lds, const Gemm g, const Sched& S, const Epi& E) {
;     ...
;         for (int t = 0; t < nt; t += 2) {
;     ...
;             PG8_WAIT_V(8); PG8_WAIT_L(0); PG8_BAR; PG8_MMA(0, 0, At, B0); PG8_MMA(0, 1, At, B1); PG8_BAR; PG8_SCHED;
;             PG8_LDA(At, 1, 1); PG8_STAGE(PG8_SB(1, 0), b3, voffB); PG8_STAGE(PG8_SB(1, 1), b3 + hstep, voffB); PG8_STAGE(PG8_SA(1, 0), a3, voffA);
;             PG8_WAIT_V(8); PG8_WAIT_L(0); PG8_BAR; PG8_MMA(1, 0, At, B0); PG8_MMA(1, 1, At, B1); PG8_BAR; PG8_SCHED;
	s_add_i32 s18, vcc_hi, s88
	v_lshl_add_u64 v[190:191], v[190:191], 0, s[16:17]
	s_mov_b32 m0, s18
	ds_read_b128 v[186:189], v198 offset:49152
	ds_read_b128 v[202:205], v198 offset:50176
	ds_read_b128 v[208:211], v198 offset:51200
	ds_read_b128 v[212:215], v198 offset:52224
	ds_read_b128 v[216:219], v198 offset:53248
	ds_read_b128 v[220:223], v198 offset:54272
	ds_read_b128 v[224:227], v198 offset:55296
	ds_read_b128 v[228:231], v198 offset:56320
	global_load_lds_dwordx4 v[190:191], off
	s_add_i32 m0, s18, 0x2000
	s_add_u32 s18, s30, 0x40080
	v_lshl_add_u64 v[190:191], v[232:233], 0, s[16:17]
	s_addc_u32 s19, s31, 0
	s_add_i32 s30, s52, s88
	global_load_lds_dwordx4 v[190:191], off
	v_lshl_add_u64 v[190:191], s[18:19], 0, v[148:149]
	s_mov_b32 m0, s30
	s_nop 0
	global_load_lds_dwordx4 v[190:191], off
	v_lshl_add_u64 v[190:191], s[18:19], 0, v[152:153]
	s_add_i32 m0, s30, 0x2000
	s_nop 0
	global_load_lds_dwordx4 v[190:191], off
	v_lshl_add_u64 v[190:191], v[234:235], 0, s[16:17]
	s_mov_b32 m0, s24
	s_nop 0
	global_load_lds_dwordx4 v[190:191], off
	v_lshl_add_u64 v[190:191], v[238:239], 0, s[16:17]
	s_mov_b32 m0, s25
	s_nop 0
	global_load_lds_dwordx4 v[190:191], off
	s_waitcnt vmcnt(8)
	s_waitcnt lgkmcnt(0)
	s_barrier
	s_setprio 1
	s_waitcnt lgkmcnt(0)
	v_mfma_f32_16x16x32_bf16 v[62:65], v[130:133], v[186:189], v[62:65]
	v_mfma_f32_16x16x32_bf16 v[58:61], v[138:141], v[186:189], v[58:61]
	v_mfma_f32_16x16x32_bf16 v[46:49], v[130:133], v[208:211], v[46:49]
	v_mfma_f32_16x16x32_bf16 v[42:45], v[138:141], v[208:211], v[42:45]
	v_mfma_f32_16x16x32_bf16 v[30:33], v[130:133], v[216:219], v[30:33]
	v_mfma_f32_16x16x32_bf16 v[26:29], v[138:141], v[216:219], v[26:29]
	v_mfma_f32_16x16x32_bf16 v[14:17], v[130:133], v[224:227], v[14:17]
	v_mfma_f32_16x16x32_bf16 v[10:13], v[138:141], v[224:227], v[10:13]
	v_mfma_f32_16x16x32_bf16 v[62:65], v[134:137], v[202:205], v[62:65]
	v_mfma_f32_16x16x32_bf16 v[58:61], v[142:145], v[202:205], v[58:61]
	v_mfma_f32_16x16x32_bf16 v[46:49], v[134:137], v[212:215], v[46:49]
	v_mfma_f32_16x16x32_bf16 v[42:45], v[142:145], v[212:215], v[42:45]
	v_mfma_f32_16x16x32_bf16 v[30:33], v[134:137], v[220:223], v[30:33]
	v_mfma_f32_16x16x32_bf16 v[26:29], v[142:145], v[220:223], v[26:29]
	v_mfma_f32_16x16x32_bf16 v[14:17], v[134:137], v[228:231], v[14:17]
	v_mfma_f32_16x16x32_bf16 v[10:13], v[142:145], v[228:231], v[10:13]
	s_setprio 0
	s_setprio 1
	v_mfma_f32_16x16x32_bf16 v[54:57], v[170:173], v[186:189], v[54:57]
	v_mfma_f32_16x16x32_bf16 v[50:53], v[178:181], v[186:189], v[50:53]
	v_mfma_f32_16x16x32_bf16 v[38:41], v[170:173], v[208:211], v[38:41]
	v_mfma_f32_16x16x32_bf16 v[34:37], v[178:181], v[208:211], v[34:37]
	v_mfma_f32_16x16x32_bf16 v[22:25], v[170:173], v[216:219], v[22:25]
	v_mfma_f32_16x16x32_bf16 v[18:21], v[178:181], v[216:219], v[18:21]
	v_mfma_f32_16x16x32_bf16 v[6:9], v[170:173], v[224:227], v[6:9]
	v_mfma_f32_16x16x32_bf16 v[2:5], v[178:181], v[224:227], v[2:5]
	v_mfma_f32_16x16x32_bf16 v[54:57], v[174:177], v[202:205], v[54:57]
	v_mfma_f32_16x16x32_bf16 v[50:53], v[182:185], v[202:205], v[50:53]
	v_mfma_f32_16x16x32_bf16 v[38:41], v[174:177], v[212:215], v[38:41]
	v_mfma_f32_16x16x32_bf16 v[34:37], v[182:185], v[212:215], v[34:37]
	v_mfma_f32_16x16x32_bf16 v[22:25], v[174:177], v[220:223], v[22:25]
	v_mfma_f32_16x16x32_bf16 v[18:21], v[182:185], v[220:223], v[18:21]
	v_mfma_f32_16x16x32_bf16 v[6:9], v[174:177], v[228:231], v[6:9]
	v_mfma_f32_16x16x32_bf16 v[2:5], v[182:185], v[228:231], v[2:5]
	s_setprio 0
	s_barrier
	s_add_i32 vcc_lo, vcc_lo, 2
	s_add_u32 s84, s84, 0x100
	s_addc_u32 s85, s85, 0
	s_add_u32 s73, s73, 0x100
	s_addc_u32 s75, s75, 0
	s_cmp_gt_u32 vcc_lo, 13
	s_cbranch_scc1 .Lpeel_done_141
.LBB0_141:
	ds_read_b128 v[130:133], v196
	ds_read_b128 v[134:137], v196 offset:1024
	ds_read_b128 v[138:141], v196 offset:2048
	ds_read_b128 v[142:145], v196 offset:3072
	s_waitcnt lgkmcnt(0)
	ds_read_b128 v[170:173], v197
	ds_read_b128 v[174:177], v197 offset:1024
	ds_read_b128 v[178:181], v197 offset:2048
	ds_read_b128 v[182:185], v197 offset:3072
	s_add_u32 s18, s84, 0xfffc0080
	s_addc_u32 s19, s85, -1
	s_cmp_eq_u32 vcc_lo, 12
	s_cselect_b32 s87, s7, s19
	s_cselect_b32 s86, s9, s18
	s_cselect_b32 s31, s10, s75
	s_cselect_b32 s30, s69, s73
	v_lshl_add_u64 v[190:191], s[84:85], 0, v[162:163]
	s_add_i32 m0, s91, 0xc000
	ds_read_b128 v[186:189], v198
	ds_read_b128 v[202:205], v198 offset:1024
	ds_read_b128 v[208:211], v198 offset:2048
	ds_read_b128 v[212:215], v198 offset:3072
	ds_read_b128 v[216:219], v198 offset:4096
	ds_read_b128 v[220:223], v198 offset:5120
	ds_read_b128 v[224:227], v198 offset:6144
	ds_read_b128 v[228:231], v198 offset:7168
	global_load_lds_dwordx4 v[190:191], off
	v_lshl_add_u64 v[190:191], s[84:85], 0, v[164:165]
	s_add_i32 m0, s91, 0xe000
	s_nop 0
	global_load_lds_dwordx4 v[190:191], off
	s_waitcnt vmcnt(8)
	s_waitcnt lgkmcnt(0)
	s_barrier
; #define PG8_STAGE(bufoff, gbase, voff) do { _Pragma("unroll") for (int _i = 0; _i < 2; ++_i) \
;         __builtin_amdgcn_global_load_lds((const unsigned*)((const char*)(gbase) + (voff)[_i]), (PG8_LAS unsigned*)(lds + (bufoff) + ldsw + _i * 8192), 16, 0, 0); } while (0)
; #define PG8_LDA(dst, b, h) do { _Pragma("unroll") for (int m = 0; m < 4; ++m) _Pragma("unroll") for (int k = 0; k < 2; ++k) dst[m][k] = *(const PG8_LAS bf16x8*)(lds + PG8_SA(b, h) + aoff + m * 2048 + k * 1024); } while (0)
; #define PG8_LDB(dst, b, h) do { _Pragma("unroll") for (int n = 0; n < 2; ++n) _Pragma("unroll") for (int k = 0; k < 2; ++k) dst[n][k] = *(const PG8_LAS bf16x8*)(lds + PG8_SB(b, h) + boff + n * 2048 + k * 1024); } while (0)
; #define PG8_MMA(ai, bj, At, Bt) do { __builtin_amdgcn_s_setprio(1); _Pragma("unroll") for (int m = 0; m < 4; ++m) _Pragma("unroll") for (int n = 0; n < 2; ++n) _Pragma("unroll") for (int k = 0; k < 2; ++k) \
;         acc[ai][bj][m][n] = __builtin_amdgcn_mfma_f32_16x16x32_bf16(Bt[n][k], At[m][k], acc[ai][bj][m][n], 0, 0, 0); __builtin_amdgcn_s_setprio(0); } while (0)
; #define PG8_WAIT_V(n) asm volatile("s_waitcnt vmcnt(" #n ")" ::: "memory")
; #define PG8_WAIT_L(n) asm volatile("s_waitcnt lgkmcnt(" #n ")" ::: "memory")
; #define PG8_BAR __builtin_amdgcn_s_barrier()
; #define PG8_SCHED __builtin_amdgcn_sched_barrier(0)
; template <class Epi, class Sched, bool ALIGN_EPI = false, bool SP2 = false>
; __device__ __forceinline__ void gemm_phase(PG8_LAS unsigned char* lds, const Gemm g, const Sched& S, const Epi& E) {
;     ...
;             PG8_LDB(B0, 0, 0); PG8_LDB(B1, 0, 1); PG8_SCHED; PG8_LDA(At, 0, 0); PG8_STAGE(PG8_SA(1, 1), a1 + hstep, voffA);
;             PG8_WAIT_V(8); PG8_WAIT_L(0); PG8_BAR; PG8_MMA(0, 0, At, B0); PG8_MMA(0, 1, At, B1); PG8_BAR; PG8_SCHED;
;             PG8_LDA(At, 0, 1); PG8_STAGE(PG8_SB(0, 0), b2, voffB); PG8_STAGE(PG8_SB(0, 1), b2 + hstep, voffB); PG8_STAGE(PG8_SA(0, 0), a2, voffA);
;             PG8_WAIT_V(8); PG8_WAIT_L(0); PG8_BAR; PG8_MMA(1, 0, At, B0); PG8_MMA(1, 1, At, B1); PG8_BAR; PG8_SCHED;
	s_setprio 1
	s_waitcnt lgkmcnt(0)
	v_mfma_f32_16x16x32_bf16 v[126:129], v[130:133], v[186:189], v[126:129]
	v_mfma_f32_16x16x32_bf16 v[122:125], v[138:141], v[186:189], v[122:125]
	v_mfma_f32_16x16x32_bf16 v[110:113], v[130:133], v[208:211], v[110:113]
	v_mfma_f32_16x16x32_bf16 v[106:109], v[138:141], v[208:211], v[106:109]
	v_mfma_f32_16x16x32_bf16 v[94:97], v[130:133], v[216:219], v[94:97]
	v_mfma_f32_16x16x32_bf16 v[90:93], v[138:141], v[216:219], v[90:93]
	v_mfma_f32_16x16x32_bf16 v[78:81], v[130:133], v[224:227], v[78:81]
	v_mfma_f32_16x16x32_bf16 v[74:77], v[138:141], v[224:227], v[74:77]
	v_mfma_f32_16x16x32_bf16 v[126:129], v[134:137], v[202:205], v[126:129]
	v_mfma_f32_16x16x32_bf16 v[122:125], v[142:145], v[202:205], v[122:125]
	v_mfma_f32_16x16x32_bf16 v[110:113], v[134:137], v[212:215], v[110:113]
	v_mfma_f32_16x16x32_bf16 v[106:109], v[142:145], v[212:215], v[106:109]
	v_mfma_f32_16x16x32_bf16 v[94:97], v[134:137], v[220:223], v[94:97]
	v_mfma_f32_16x16x32_bf16 v[90:93], v[142:145], v[220:223], v[90:93]
	v_mfma_f32_16x16x32_bf16 v[78:81], v[134:137], v[228:231], v[78:81]
	v_mfma_f32_16x16x32_bf16 v[74:77], v[142:145], v[228:231], v[74:77]
	s_setprio 0
	s_setprio 1
	v_mfma_f32_16x16x32_bf16 v[118:121], v[170:173], v[186:189], v[118:121]
	v_mfma_f32_16x16x32_bf16 v[114:117], v[178:181], v[186:189], v[114:117]
	v_mfma_f32_16x16x32_bf16 v[102:105], v[170:173], v[208:211], v[102:105]
	v_mfma_f32_16x16x32_bf16 v[98:101], v[178:181], v[208:211], v[98:101]
	v_mfma_f32_16x16x32_bf16 v[86:89], v[170:173], v[216:219], v[86:89]
	v_mfma_f32_16x16x32_bf16 v[82:85], v[178:181], v[216:219], v[82:85]
	v_mfma_f32_16x16x32_bf16 v[70:73], v[170:173], v[224:227], v[70:73]
	v_mfma_f32_16x16x32_bf16 v[66:69], v[178:181], v[224:227], v[66:69]
	v_mfma_f32_16x16x32_bf16 v[118:121], v[174:177], v[202:205], v[118:121]
	v_mfma_f32_16x16x32_bf16 v[114:117], v[182:185], v[202:205], v[114:117]
	v_mfma_f32_16x16x32_bf16 v[102:105], v[174:177], v[212:215], v[102:105]
	v_mfma_f32_16x16x32_bf16 v[98:101], v[182:185], v[212:215], v[98:101]
	v_mfma_f32_16x16x32_bf16 v[86:89], v[174:177], v[220:223], v[86:89]
	v_mfma_f32_16x16x32_bf16 v[82:85], v[182:185], v[220:223], v[82:85]
	v_mfma_f32_16x16x32_bf16 v[70:73], v[174:177], v[228:231], v[70:73]
	v_mfma_f32_16x16x32_bf16 v[66:69], v[182:185], v[228:231], v[66:69]
	s_setprio 0
	s_barrier
	s_add_i32 s18, s58, s88
	v_lshl_add_u64 v[190:191], s[30:31], 0, v[148:149]
	s_mov_b32 m0, s18
	ds_read_b128 v[186:189], v198 offset:16384
	ds_read_b128 v[202:205], v198 offset:17408
	ds_read_b128 v[208:211], v198 offset:18432
	ds_read_b128 v[212:215], v198 offset:19456
	ds_read_b128 v[216:219], v198 offset:20480
	ds_read_b128 v[220:223], v198 offset:21504
	ds_read_b128 v[224:227], v198 offset:22528
	ds_read_b128 v[228:231], v198 offset:23552
	global_load_lds_dwordx4 v[190:191], off
	s_add_i32 m0, s18, 0x2000
	s_add_u32 s18, s30, 0x40000
	v_lshl_add_u64 v[232:233], s[30:31], 0, v[152:153]
	s_addc_u32 s19, s31, 0
	s_add_i32 vcc_hi, s59, s88
	global_load_lds_dwordx4 v[232:233], off
	v_lshl_add_u64 v[234:235], s[18:19], 0, v[148:149]
	s_mov_b32 m0, vcc_hi
	v_lshl_add_u64 v[238:239], s[86:87], 0, v[150:151]
	global_load_lds_dwordx4 v[234:235], off
	v_lshl_add_u64 v[234:235], s[18:19], 0, v[152:153]
	s_add_i32 m0, vcc_hi, 0x2000
	s_nop 0
	global_load_lds_dwordx4 v[234:235], off
	v_lshl_add_u64 v[234:235], s[86:87], 0, v[146:147]
	s_mov_b32 m0, s91
	s_nop 0
	global_load_lds_dwordx4 v[234:235], off
	s_mov_b32 m0, s92
	s_nop 0
	global_load_lds_dwordx4 v[238:239], off
	s_waitcnt vmcnt(8)
	s_waitcnt lgkmcnt(0)
	s_barrier
	s_setprio 1
	s_waitcnt lgkmcnt(0)
	v_mfma_f32_16x16x32_bf16 v[62:65], v[130:133], v[186:189], v[62:65]
	v_mfma_f32_16x16x32_bf16 v[58:61], v[138:141], v[186:189], v[58:61]
	v_mfma_f32_16x16x32_bf16 v[46:49], v[130:133], v[208:211], v[46:49]
	v_mfma_f32_16x16x32_bf16 v[42:45], v[138:141], v[208:211], v[42:45]
	v_mfma_f32_16x16x32_bf16 v[30:33], v[130:133], v[216:219], v[30:33]
	v_mfma_f32_16x16x32_bf16 v[26:29], v[138:141], v[216:219], v[26:29]
	v_mfma_f32_16x16x32_bf16 v[14:17], v[130:133], v[224:227], v[14:17]
	v_mfma_f32_16x16x32_bf16 v[10:13], v[138:141], v[224:227], v[10:13]
	v_mfma_f32_16x16x32_bf16 v[62:65], v[134:137], v[202:205], v[62:65]
	v_mfma_f32_16x16x32_bf16 v[58:61], v[142:145], v[202:205], v[58:61]
	v_mfma_f32_16x16x32_bf16 v[46:49], v[134:137], v[212:215], v[46:49]
	v_mfma_f32_16x16x32_bf16 v[42:45], v[142:145], v[212:215], v[42:45]
	v_mfma_f32_16x16x32_bf16 v[30:33], v[134:137], v[220:223], v[30:33]
	v_mfma_f32_16x16x32_bf16 v[26:29], v[142:145], v[220:223], v[26:29]
	v_mfma_f32_16x16x32_bf16 v[14:17], v[134:137], v[228:231], v[14:17]
	v_mfma_f32_16x16x32_bf16 v[10:13], v[142:145], v[228:231], v[10:13]
	s_setprio 0
	s_setprio 1
	v_mfma_f32_16x16x32_bf16 v[54:57], v[170:173], v[186:189], v[54:57]
	v_mfma_f32_16x16x32_bf16 v[50:53], v[178:181], v[186:189], v[50:53]
	v_mfma_f32_16x16x32_bf16 v[38:41], v[170:173], v[208:211], v[38:41]
	v_mfma_f32_16x16x32_bf16 v[34:37], v[178:181], v[208:211], v[34:37]
	v_mfma_f32_16x16x32_bf16 v[22:25], v[170:173], v[216:219], v[22:25]
	v_mfma_f32_16x16x32_bf16 v[18:21], v[178:181], v[216:219], v[18:21]
	v_mfma_f32_16x16x32_bf16 v[6:9], v[170:173], v[224:227], v[6:9]
	v_mfma_f32_16x16x32_bf16 v[2:5], v[178:181], v[224:227], v[2:5]
	v_mfma_f32_16x16x32_bf16 v[54:57], v[174:177], v[202:205], v[54:57]
	v_mfma_f32_16x16x32_bf16 v[50:53], v[182:185], v[202:205], v[50:53]
	v_mfma_f32_16x16x32_bf16 v[38:41], v[174:177], v[212:215], v[38:41]
	v_mfma_f32_16x16x32_bf16 v[34:37], v[182:185], v[212:215], v[34:37]
	v_mfma_f32_16x16x32_bf16 v[22:25], v[174:177], v[220:223], v[22:25]
	v_mfma_f32_16x16x32_bf16 v[18:21], v[182:185], v[220:223], v[18:21]
	v_mfma_f32_16x16x32_bf16 v[6:9], v[174:177], v[228:231], v[6:9]
	v_mfma_f32_16x16x32_bf16 v[2:5], v[182:185], v[228:231], v[2:5]
	s_setprio 0
	s_barrier
; #define PG8_STAGE(bufoff, gbase, voff) do { _Pragma("unroll") for (int _i = 0; _i < 2; ++_i) \
;         __builtin_amdgcn_global_load_lds((const unsigned*)((const char*)(gbase) + (voff)[_i]), (PG8_LAS unsigned*)(lds + (bufoff) + ldsw + _i * 8192), 16, 0, 0); } while (0)
; #define PG8_LDA(dst, b, h) do { _Pragma("unroll") for (int m = 0; m < 4; ++m) _Pragma("unroll") for (int k = 0; k < 2; ++k) dst[m][k] = *(const PG8_LAS bf16x8*)(lds + PG8_SA(b, h) + aoff + m * 2048 + k * 1024); } while (0)
; #define PG8_LDB(dst, b, h) do { _Pragma("unroll") for (int n = 0; n < 2; ++n) _Pragma("unroll") for (int k = 0; k < 2; ++k) dst[n][k] = *(const PG8_LAS bf16x8*)(lds + PG8_SB(b, h) + boff + n * 2048 + k * 1024); } while (0)
; #define PG8_MMA(ai, bj, At, Bt) do { __builtin_amdgcn_s_setprio(1); _Pragma("unroll") for (int m = 0; m < 4; ++m) _Pragma("unroll") for (int n = 0; n < 2; ++n) _Pragma("unroll") for (int k = 0; k < 2; ++k) \
;         acc[ai][bj][m][n] = __builtin_amdgcn_mfma_f32_16x16x32_bf16(Bt[n][k], At[m][k], acc[ai][bj][m][n], 0, 0, 0); __builtin_amdgcn_s_setprio(0); } while (0)
; #define PG8_WAIT_V(n) asm volatile("s_waitcnt vmcnt(" #n ")" ::: "memory")
; #define PG8_WAIT_L(n) asm volatile("s_waitcnt lgkmcnt(" #n ")" ::: "memory")
; #define PG8_BAR __builtin_amdgcn_s_barrier()
; #define PG8_SCHED __builtin_amdgcn_sched_barrier(0)
; template <class Epi, class Sched, bool ALIGN_EPI = false, bool SP2 = false>
; __device__ __forceinline__ void gemm_phase(PG8_LAS unsigned char* lds, const Gemm g, const Sched& S, const Epi& E) {
;     ...
;             PG8_LDB(B0, 1, 0); PG8_LDB(B1, 1, 1); PG8_SCHED; PG8_LDA(At, 1, 0); PG8_STAGE(PG8_SA(0, 1), a2 + hstep, voffA);
;             PG8_WAIT_V(8); PG8_WAIT_L(0); PG8_BAR; PG8_MMA(0, 0, At, B0); PG8_MMA(0, 1, At, B1); PG8_BAR; PG8_SCHED;
;             PG8_LDA(At, 1, 1); PG8_STAGE(PG8_SB(1, 0), b3, voffB); PG8_STAGE(PG8_SB(1, 1), b3 + hstep, voffB); PG8_STAGE(PG8_SA(1, 0), a3, voffA);
	s_add_i32 vcc_hi, 0, 0x18000
	s_add_i32 s52, 0, 0x1c000
	v_add_u32_e32 v142, vcc_hi, v157
	v_add_u32_e32 v154, s52, v157
	ds_read_b128 v[130:133], v142
	ds_read_b128 v[134:137], v142 offset:1024
	ds_read_b128 v[138:141], v142 offset:2048
	ds_read_b128 v[142:145], v142 offset:3072
	ds_read_b128 v[170:173], v154
	ds_read_b128 v[174:177], v154 offset:1024
	ds_read_b128 v[178:181], v154 offset:2048
	ds_read_b128 v[182:185], v154 offset:3072
	s_add_u32 s18, s86, 0x40000
	s_addc_u32 s19, s87, 0
	s_mov_b32 m0, s93
	v_lshl_add_u64 v[240:241], s[18:19], 0, v[146:147]
	ds_read_b128 v[186:189], v198 offset:32768
	ds_read_b128 v[202:205], v198 offset:33792
	ds_read_b128 v[208:211], v198 offset:34816
	ds_read_b128 v[212:215], v198 offset:35840
	ds_read_b128 v[216:219], v198 offset:36864
	ds_read_b128 v[220:223], v198 offset:37888
	ds_read_b128 v[224:227], v198 offset:38912
	ds_read_b128 v[228:231], v198 offset:39936
	global_load_lds_dwordx4 v[240:241], off
	v_lshl_add_u64 v[240:241], s[18:19], 0, v[150:151]
	s_mov_b32 m0, s95
	s_nop 0
	global_load_lds_dwordx4 v[240:241], off
	s_waitcnt vmcnt(8)
	s_waitcnt lgkmcnt(0)
	s_barrier
	s_setprio 1
	s_waitcnt lgkmcnt(0)
	v_mfma_f32_16x16x32_bf16 v[126:129], v[130:133], v[186:189], v[126:129]
	v_mfma_f32_16x16x32_bf16 v[122:125], v[138:141], v[186:189], v[122:125]
	v_mfma_f32_16x16x32_bf16 v[110:113], v[130:133], v[208:211], v[110:113]
	v_mfma_f32_16x16x32_bf16 v[106:109], v[138:141], v[208:211], v[106:109]
	v_mfma_f32_16x16x32_bf16 v[94:97], v[130:133], v[216:219], v[94:97]
	v_mfma_f32_16x16x32_bf16 v[90:93], v[138:141], v[216:219], v[90:93]
	v_mfma_f32_16x16x32_bf16 v[78:81], v[130:133], v[224:227], v[78:81]
	v_mfma_f32_16x16x32_bf16 v[74:77], v[138:141], v[224:227], v[74:77]
	v_mfma_f32_16x16x32_bf16 v[126:129], v[134:137], v[202:205], v[126:129]
	v_mfma_f32_16x16x32_bf16 v[122:125], v[142:145], v[202:205], v[122:125]
	v_mfma_f32_16x16x32_bf16 v[110:113], v[134:137], v[212:215], v[110:113]
	v_mfma_f32_16x16x32_bf16 v[106:109], v[142:145], v[212:215], v[106:109]
	v_mfma_f32_16x16x32_bf16 v[94:97], v[134:137], v[220:223], v[94:97]
	v_mfma_f32_16x16x32_bf16 v[90:93], v[142:145], v[220:223], v[90:93]
	v_mfma_f32_16x16x32_bf16 v[78:81], v[134:137], v[228:231], v[78:81]
	v_mfma_f32_16x16x32_bf16 v[74:77], v[142:145], v[228:231], v[74:77]
	s_setprio 0
	s_setprio 1
	v_mfma_f32_16x16x32_bf16 v[118:121], v[170:173], v[186:189], v[118:121]
	v_mfma_f32_16x16x32_bf16 v[114:117], v[178:181], v[186:189], v[114:117]
	v_mfma_f32_16x16x32_bf16 v[102:105], v[170:173], v[208:211], v[102:105]
	v_mfma_f32_16x16x32_bf16 v[98:101], v[178:181], v[208:211], v[98:101]
	v_mfma_f32_16x16x32_bf16 v[86:89], v[170:173], v[216:219], v[86:89]
	v_mfma_f32_16x16x32_bf16 v[82:85], v[178:181], v[216:219], v[82:85]
	v_mfma_f32_16x16x32_bf16 v[70:73], v[170:173], v[224:227], v[70:73]
	v_mfma_f32_16x16x32_bf16 v[66:69], v[178:181], v[224:227], v[66:69]
	v_mfma_f32_16x16x32_bf16 v[118:121], v[174:177], v[202:205], v[118:121]
	v_mfma_f32_16x16x32_bf16 v[114:117], v[182:185], v[202:205], v[114:117]
	v_mfma_f32_16x16x32_bf16 v[102:105], v[174:177], v[212:215], v[102:105]
	v_mfma_f32_16x16x32_bf16 v[98:101], v[182:185], v[212:215], v[98:101]
	v_mfma_f32_16x16x32_bf16 v[86:89], v[174:177], v[220:223], v[86:89]
	v_mfma_f32_16x16x32_bf16 v[82:85], v[182:185], v[220:223], v[82:85]
	v_mfma_f32_16x16x32_bf16 v[70:73], v[174:177], v[228:231], v[70:73]
	v_mfma_f32_16x16x32_bf16 v[66:69], v[182:185], v[228:231], v[66:69]
	s_setprio 0
	s_barrier
	s_add_i32 s18, vcc_hi, s88
	v_lshl_add_u64 v[190:191], v[190:191], 0, s[16:17]
	s_mov_b32 m0, s18
	ds_read_b128 v[186:189], v198 offset:49152
	ds_read_b128 v[202:205], v198 offset:50176
	ds_read_b128 v[208:211], v198 offset:51200
	ds_read_b128 v[212:215], v198 offset:52224
	ds_read_b128 v[216:219], v198 offset:53248
	ds_read_b128 v[220:223], v198 offset:54272
	ds_read_b128 v[224:227], v198 offset:55296
	ds_read_b128 v[228:231], v198 offset:56320
	global_load_lds_dwordx4 v[190:191], off
	s_add_i32 m0, s18, 0x2000
	s_add_u32 s18, s30, 0x40080
	v_lshl_add_u64 v[190:191], v[232:233], 0, s[16:17]
	s_addc_u32 s19, s31, 0
	s_add_i32 s30, s52, s88
	global_load_lds_dwordx4 v[190:191], off
	v_lshl_add_u64 v[190:191], s[18:19], 0, v[148:149]
	s_mov_b32 m0, s30
	s_nop 0
	global_load_lds_dwordx4 v[190:191], off
	v_lshl_add_u64 v[190:191], s[18:19], 0, v[152:153]
	s_add_i32 m0, s30, 0x2000
	s_nop 0
	global_load_lds_dwordx4 v[190:191], off
	v_lshl_add_u64 v[190:191], v[234:235], 0, s[16:17]
	s_mov_b32 m0, s24
	s_nop 0
	global_load_lds_dwordx4 v[190:191], off
	v_lshl_add_u64 v[190:191], v[238:239], 0, s[16:17]
	s_mov_b32 m0, s25
	s_nop 0
	global_load_lds_dwordx4 v[190:191], off
	s_waitcnt vmcnt(8)
	s_waitcnt lgkmcnt(0)
	s_barrier
; #define PG8_WAIT_V(n) asm volatile("s_waitcnt vmcnt(" #n ")" ::: "memory")
; #define PG8_BAR __builtin_amdgcn_s_barrier()
;     __device__ __forceinline__ void operator()(const f32x4 (&acc)[2][2][4][2], const Unit& u, int wr, int wc, int fr, int fq) const {
;     ...
;         } else {
; #pragma unroll
;             for (int ai = 0; ai < 2; ++ai)
; #pragma unroll
;                 for (int m = 0; m < 4; ++m) r0s[ai][m] = SS0[row0 + ai * HALF + m * 16];
; #pragma unroll
;             for (int ai = 0; ai < 2; ++ai)
; #pragma unroll
;                 for (int m = 0; m < 4; ++m) r0s[ai][m] = rsqrtf(r0s[ai][m] * (1.f / DM) + EPS);
;         }
; template <class Epi, class Sched, bool ALIGN_EPI = false, bool SP2 = false>
; __device__ __forceinline__ void gemm_phase(PG8_LAS unsigned char* lds, const Gemm g, const Sched& S, const Epi& E) {
;     ...
;             PG8_WAIT_V(8); PG8_WAIT_L(0); PG8_BAR; PG8_MMA(1, 0, At, B0); PG8_MMA(1, 1, At, B1); PG8_BAR; PG8_SCHED;
;             } else {
;             PG8_LDB(B0, 0, 0); PG8_SCHED; PG8_LDA(At, 0, 0); PG8_STAGE(PG8_SA(1, 1), a1 + hstep, voffA);
;             PG8_WAIT_L(8); PG8_BAR; PG8_WAIT_L(0); PG8_MMA(0, 0, At, B0); PG8_BAR; PG8_SCHED;
;             PG8_LDB(B1, 0, 1); PG8_STAGE(PG8_SB(0, 0), b2, voffB);
;             PG8_BAR; PG8_WAIT_L(0); PG8_MMA(0, 1, At, B1); PG8_BAR;
;             PG8_LDA(At, 0, 1); PG8_STAGE(PG8_SA(0, 0), a2, voffA);
;             PG8_BAR; PG8_WAIT_L(0); PG8_MMA(1, 0, At, B0); PG8_BAR; PG8_SCHED;
;             PG8_STAGE(PG8_SB(0, 1), b2 + hstep, voffB);
;             PG8_WAIT_V(6); PG8_BAR; PG8_MMA(1, 1, At, B1); PG8_BAR;
;             PG8_LDB(B0, 1, 0); PG8_SCHED; PG8_LDA(At, 1, 0); PG8_STAGE(PG8_SA(0, 1), a2 + hstep, voffA);
;             PG8_WAIT_L(8); PG8_BAR; PG8_WAIT_L(0); PG8_MMA(0, 0, At, B0); PG8_BAR; PG8_SCHED;
;             PG8_LDB(B1, 1, 1); PG8_STAGE(PG8_SB(1, 0), b3, voffB);
;             PG8_BAR; PG8_WAIT_L(0); PG8_MMA(0, 1, At, B1); PG8_BAR;
;             PG8_LDA(At, 1, 1); PG8_STAGE(PG8_SA(1, 0), a3, voffA);
;             PG8_BAR; PG8_WAIT_L(0); PG8_MMA(1, 0, At, B0); PG8_BAR; PG8_SCHED;
;             PG8_STAGE(PG8_SB(1, 1), b3 + hstep, voffB);
;             PG8_WAIT_V(6); PG8_BAR; PG8_MMA(1, 1, At, B1); PG8_BAR;
;             }
;         }
;         if constexpr (ALIGN_EPI) { if (wr == 0) PG8_BAR; }
;         if constexpr (!Epi::AFTER_DRAIN) { E(acc, cur, wr, wc, fr, fq); S.done(cur); }
	s_setprio 1
	s_waitcnt lgkmcnt(0)
	v_mfma_f32_16x16x32_bf16 v[62:65], v[130:133], v[186:189], v[62:65]
	v_mfma_f32_16x16x32_bf16 v[58:61], v[138:141], v[186:189], v[58:61]
	v_mfma_f32_16x16x32_bf16 v[46:49], v[130:133], v[208:211], v[46:49]
	v_mfma_f32_16x16x32_bf16 v[42:45], v[138:141], v[208:211], v[42:45]
	v_mfma_f32_16x16x32_bf16 v[30:33], v[130:133], v[216:219], v[30:33]
	v_mfma_f32_16x16x32_bf16 v[26:29], v[138:141], v[216:219], v[26:29]
	v_mfma_f32_16x16x32_bf16 v[14:17], v[130:133], v[224:227], v[14:17]
	v_mfma_f32_16x16x32_bf16 v[10:13], v[138:141], v[224:227], v[10:13]
	v_mfma_f32_16x16x32_bf16 v[62:65], v[134:137], v[202:205], v[62:65]
	v_mfma_f32_16x16x32_bf16 v[58:61], v[142:145], v[202:205], v[58:61]
	v_mfma_f32_16x16x32_bf16 v[46:49], v[134:137], v[212:215], v[46:49]
	v_mfma_f32_16x16x32_bf16 v[42:45], v[142:145], v[212:215], v[42:45]
	v_mfma_f32_16x16x32_bf16 v[30:33], v[134:137], v[220:223], v[30:33]
	v_mfma_f32_16x16x32_bf16 v[26:29], v[142:145], v[220:223], v[26:29]
	v_mfma_f32_16x16x32_bf16 v[14:17], v[134:137], v[228:231], v[14:17]
	v_mfma_f32_16x16x32_bf16 v[10:13], v[142:145], v[228:231], v[10:13]
	s_setprio 0
	s_setprio 1
	v_mfma_f32_16x16x32_bf16 v[54:57], v[170:173], v[186:189], v[54:57]
	v_mfma_f32_16x16x32_bf16 v[50:53], v[178:181], v[186:189], v[50:53]
	v_mfma_f32_16x16x32_bf16 v[38:41], v[170:173], v[208:211], v[38:41]
	v_mfma_f32_16x16x32_bf16 v[34:37], v[178:181], v[208:211], v[34:37]
	v_mfma_f32_16x16x32_bf16 v[22:25], v[170:173], v[216:219], v[22:25]
	v_mfma_f32_16x16x32_bf16 v[18:21], v[178:181], v[216:219], v[18:21]
	v_mfma_f32_16x16x32_bf16 v[6:9], v[170:173], v[224:227], v[6:9]
	v_mfma_f32_16x16x32_bf16 v[2:5], v[178:181], v[224:227], v[2:5]
	v_mfma_f32_16x16x32_bf16 v[54:57], v[174:177], v[202:205], v[54:57]
	v_mfma_f32_16x16x32_bf16 v[50:53], v[182:185], v[202:205], v[50:53]
	v_mfma_f32_16x16x32_bf16 v[38:41], v[174:177], v[212:215], v[38:41]
	v_mfma_f32_16x16x32_bf16 v[34:37], v[182:185], v[212:215], v[34:37]
	v_mfma_f32_16x16x32_bf16 v[22:25], v[174:177], v[220:223], v[22:25]
	v_mfma_f32_16x16x32_bf16 v[18:21], v[182:185], v[220:223], v[18:21]
	v_mfma_f32_16x16x32_bf16 v[6:9], v[174:177], v[228:231], v[6:9]
	v_mfma_f32_16x16x32_bf16 v[2:5], v[182:185], v[228:231], v[2:5]
	s_setprio 0
	s_barrier
	s_add_i32 vcc_lo, vcc_lo, 2
	s_add_u32 s84, s84, 0x100
	s_addc_u32 s85, s85, 0
	s_add_u32 s73, s73, 0x100
	s_addc_u32 s75, s75, 0
	s_cmp_gt_u32 vcc_lo, 13
	s_cbranch_scc0 .LBB0_141
.Lpeel_done_141:
	s_and_b64 vcc, exec, s[26:27]
	s_cbranch_vccz .LBB0_144
	s_barrier
.LBB0_144:
	s_lshl_b32 s69, s6, 8
	s_add_i32 s69, s69, s96
	v_or_b32_e32 v170, s69, v1
	s_mov_b64 s[30:31], -1
	s_cmp_eq_u32 s6, s71
	v_ashrrev_i32_e32 v171, 31, v170
	s_cbranch_scc1 .LBB0_153
	v_lshl_add_u64 v[130:131], v[170:171], 2, s[14:15]
	global_load_dword v132, v[130:131], off
	global_load_dword v133, v[130:131], off offset:64
	global_load_dword v134, v[130:131], off offset:128
	global_load_dword v135, v[130:131], off offset:192
	global_load_dword v136, v[130:131], off offset:512
	global_load_dword v137, v[130:131], off offset:576
	global_load_dword v138, v[130:131], off offset:640
	global_load_dword v139, v[130:131], off offset:704
	s_mov_b32 s6, 0x358637bd
	v_mov_b64_e32 v[130:131], s[6:7]
	s_waitcnt vmcnt(0)
	v_pk_fma_f32 v[132:133], v[132:133], s[34:35], v[130:131] op_sel_hi:[1,0,0]
	s_nop 0
	v_mul_f32_e32 v140, 0x4b800000, v132
	v_cmp_gt_f32_e64 s[6:7], s80, v132
	v_cmp_gt_f32_e32 vcc, s80, v133
	s_nop 0
	v_cndmask_b32_e64 v132, v132, v140, s[6:7]
	v_mul_f32_e32 v140, 0x4b800000, v133
	v_cndmask_b32_e32 v133, v133, v140, vcc
	v_rsq_f32_e32 v132, v132
	v_rsq_f32_e32 v133, v133
	s_nop 0
	v_pk_mul_f32 v[140:141], v[132:133], s[70:71] op_sel_hi:[1,0]
	s_nop 0
	v_cndmask_b32_e32 v179, v133, v141, vcc
	v_cndmask_b32_e64 v178, v132, v140, s[6:7]
	v_pk_fma_f32 v[132:133], v[134:135], s[34:35], v[130:131] op_sel_hi:[1,0,0]
	s_nop 0
	v_mul_f32_e32 v134, 0x4b800000, v132
	v_cmp_gt_f32_e64 s[6:7], s80, v132
	v_cmp_gt_f32_e32 vcc, s80, v133
	s_nop 0
	v_cndmask_b32_e64 v132, v132, v134, s[6:7]
	v_mul_f32_e32 v134, 0x4b800000, v133
	v_cndmask_b32_e32 v133, v133, v134, vcc
	v_rsq_f32_e32 v132, v132
	v_rsq_f32_e32 v133, v133
	s_nop 0
	v_pk_mul_f32 v[134:135], v[132:133], s[70:71] op_sel_hi:[1,0]
	s_nop 0
	v_cndmask_b32_e32 v177, v133, v135, vcc
	v_cndmask_b32_e64 v176, v132, v134, s[6:7]
	v_pk_fma_f32 v[132:133], v[136:137], s[34:35], v[130:131] op_sel_hi:[1,0,0]
	v_pk_fma_f32 v[130:131], v[138:139], s[34:35], v[130:131] op_sel_hi:[1,0,0]
	v_mul_f32_e32 v134, 0x4b800000, v132
	v_cmp_gt_f32_e64 s[6:7], s80, v132
	v_cmp_gt_f32_e32 vcc, s80, v133
	s_nop 0
	v_cndmask_b32_e64 v132, v132, v134, s[6:7]
	v_mul_f32_e32 v134, 0x4b800000, v133
	v_cndmask_b32_e32 v133, v133, v134, vcc
	v_rsq_f32_e32 v132, v132
	v_rsq_f32_e32 v133, v133
	s_nop 0
	v_pk_mul_f32 v[134:135], v[132:133], s[70:71] op_sel_hi:[1,0]
	s_nop 0
	v_cndmask_b32_e64 v174, v132, v134, s[6:7]
	v_mul_f32_e32 v132, 0x4b800000, v130
	v_cmp_gt_f32_e64 s[6:7], s80, v130
	v_cndmask_b32_e32 v175, v133, v135, vcc
	v_cmp_gt_f32_e32 vcc, s80, v131
	v_cndmask_b32_e64 v130, v130, v132, s[6:7]
	v_mul_f32_e32 v132, 0x4b800000, v131
	v_cndmask_b32_e32 v131, v131, v132, vcc
	v_rsq_f32_e32 v130, v130
	v_rsq_f32_e32 v131, v131
	s_nop 0
	v_pk_mul_f32 v[132:133], v[130:131], s[70:71] op_sel_hi:[1,0]
	s_nop 0
	v_cndmask_b32_e32 v173, v131, v133, vcc
	v_cndmask_b32_e64 v172, v130, v132, s[6:7]
	s_cbranch_execz .LBB0_154

; #define PG8_STAGE(bufoff, gbase, voff) do { _Pragma("unroll") for (int _i = 0; _i < 2; ++_i) \
;         __builtin_amdgcn_global_load_lds((const unsigned*)((const char*)(gbase) + (voff)[_i]), (PG8_LAS unsigned*)(lds + (bufoff) + ldsw + _i * 8192), 16, 0, 0); } while (0)
; #define PG8_LDA(dst, b, h) do { _Pragma("unroll") for (int m = 0; m < 4; ++m) _Pragma("unroll") for (int k = 0; k < 2; ++k) dst[m][k] = *(const PG8_LAS bf16x8*)(lds + PG8_SA(b, h) + aoff + m * 2048 + k * 1024); } while (0)
; #define PG8_LDB(dst, b, h) do { _Pragma("unroll") for (int n = 0; n < 2; ++n) _Pragma("unroll") for (int k = 0; k < 2; ++k) dst[n][k] = *(const PG8_LAS bf16x8*)(lds + PG8_SB(b, h) + boff + n * 2048 + k * 1024); } while (0)
; #define PG8_WAIT_V(n) asm volatile("s_waitcnt vmcnt(" #n ")" ::: "memory")
; #define PG8_WAIT_L(n) asm volatile("s_waitcnt lgkmcnt(" #n ")" ::: "memory")
; #define PG8_BAR __builtin_amdgcn_s_barrier()
; #define PG8_SCHED __builtin_amdgcn_sched_barrier(0)
; template <class Epi, class Sched, bool ALIGN_EPI = false, bool SP2 = false>
; __device__ __forceinline__ void gemm_phase(PG8_LAS unsigned char* lds, const Gemm g, const Sched& S, const Epi& E) {
;     ...
;         const bool has_next = S.next(ui + 1, nxt);
;         const char* nA = has_next ? (const char*)g.A + (size_t)nxt.pm * tstep : cA; const char* nB = has_next ? (const char*)g.Bt + (size_t)nxt.pn * tstep : cB;
;         for (int t = 0; t < nt; t += 2) {
;             const bool last = (t == nt - 2);
;             const char* a1 = cA + (size_t)(t + 1) * kstep;
;             const char* a2 = last ? nA : cA + (size_t)(t + 2) * kstep; const char* b2 = last ? nB : cB + (size_t)(t + 2) * kstep;
;             const char* a3 = a2 + kstep; const char* b3 = b2 + kstep;
;             if (last && has_next) S.a_ready(nxt);
;             if constexpr (SP2) {
;             PG8_LDB(B0, 0, 0); PG8_LDB(B1, 0, 1); PG8_SCHED; PG8_LDA(At, 0, 0); PG8_STAGE(PG8_SA(1, 1), a1 + hstep, voffA);
;             PG8_WAIT_V(8); PG8_WAIT_L(0); PG8_BAR; PG8_MMA(0, 0, At, B0); PG8_MMA(0, 1, At, B1); PG8_BAR; PG8_SCHED;
;             PG8_LDA(At, 0, 1); PG8_STAGE(PG8_SB(0, 0), b2, voffB); PG8_STAGE(PG8_SB(0, 1), b2 + hstep, voffB); PG8_STAGE(PG8_SA(0, 0), a2, voffA);
;             PG8_WAIT_V(8); PG8_WAIT_L(0); PG8_BAR; PG8_MMA(1, 0, At, B0); PG8_MMA(1, 1, At, B1); PG8_BAR; PG8_SCHED;
.LBB0_737:
	s_ashr_i32 s41, s40, 31
	s_lshl_b64 s[6:7], s[40:41], 19
	s_add_u32 s42, s20, s6
	s_addc_u32 s43, s21, s7
	s_and_b64 s[6:7], s[2:3], exec
	s_cselect_b32 s1, s43, s5
	s_cselect_b32 s41, s42, s4
	s_ashr_i32 s39, s38, 31
	s_lshl_b64 s[6:7], s[38:39], 19
	s_add_u32 s44, s27, s6
	s_addc_u32 s45, s35, s7
	s_and_b64 s[6:7], s[2:3], exec
	s_cselect_b32 s39, s45, s47
	s_cselect_b32 s65, s44, s46
	s_add_u32 s4, s4, 0x40080
	s_addc_u32 s5, s5, 0
	s_add_u32 s46, s46, 0x100
	s_addc_u32 s47, s47, 0
	s_mov_b32 s66, -2
	ds_read_b128 v[148:151], v195
	ds_read_b128 v[152:155], v195 offset:1024
	ds_read_b128 v[156:159], v195 offset:2048
	ds_read_b128 v[160:163], v195 offset:3072
	ds_read_b128 v[164:167], v196
	ds_read_b128 v[168:171], v196 offset:1024
	ds_read_b128 v[172:175], v196 offset:2048
	ds_read_b128 v[198:201], v196 offset:3072
	s_add_u32 s6, s4, 0xfffc0080
	s_addc_u32 s7, s5, -1
	s_cmp_eq_u32 s66, 12
	s_cselect_b32 s31, s1, s7
	s_cselect_b32 s30, s41, s6
	s_cselect_b32 s7, s39, s47
	s_cselect_b32 s6, s65, s46
	v_lshl_add_u64 v[176:177], s[4:5], 0, v[140:141]
	s_add_i32 m0, s49, 0xc000
	ds_read_b128 v[202:205], v197
	ds_read_b128 v[206:209], v197 offset:1024
	ds_read_b128 v[210:213], v197 offset:2048
	ds_read_b128 v[214:217], v197 offset:3072
	ds_read_b128 v[218:221], v197 offset:4096
	ds_read_b128 v[222:225], v197 offset:5120
	ds_read_b128 v[226:229], v197 offset:6144
	ds_read_b128 v[230:233], v197 offset:7168
	global_load_lds_dwordx4 v[176:177], off
	v_lshl_add_u64 v[176:177], s[4:5], 0, v[142:143]
	s_add_i32 m0, s49, 0xe000
	s_nop 0
	global_load_lds_dwordx4 v[176:177], off
	s_waitcnt vmcnt(8)
	s_waitcnt lgkmcnt(0)
	s_barrier
	s_setprio 1
	s_waitcnt lgkmcnt(0)
	v_mfma_f32_16x16x32_bf16 v[126:129], v[148:151], v[202:205], 0
	v_mfma_f32_16x16x32_bf16 v[118:121], v[156:159], v[202:205], 0
	v_mfma_f32_16x16x32_bf16 v[110:113], v[148:151], v[210:213], 0
	v_mfma_f32_16x16x32_bf16 v[102:105], v[156:159], v[210:213], 0
	v_mfma_f32_16x16x32_bf16 v[94:97], v[148:151], v[218:221], 0
	v_mfma_f32_16x16x32_bf16 v[86:89], v[156:159], v[218:221], 0
	v_mfma_f32_16x16x32_bf16 v[78:81], v[148:151], v[226:229], 0
	v_mfma_f32_16x16x32_bf16 v[70:73], v[156:159], v[226:229], 0
	v_mfma_f32_16x16x32_bf16 v[126:129], v[152:155], v[206:209], v[126:129]
	v_mfma_f32_16x16x32_bf16 v[118:121], v[160:163], v[206:209], v[118:121]
	v_mfma_f32_16x16x32_bf16 v[110:113], v[152:155], v[214:217], v[110:113]
	v_mfma_f32_16x16x32_bf16 v[102:105], v[160:163], v[214:217], v[102:105]
	v_mfma_f32_16x16x32_bf16 v[94:97], v[152:155], v[222:225], v[94:97]
	v_mfma_f32_16x16x32_bf16 v[86:89], v[160:163], v[222:225], v[86:89]
	v_mfma_f32_16x16x32_bf16 v[78:81], v[152:155], v[230:233], v[78:81]
	v_mfma_f32_16x16x32_bf16 v[70:73], v[160:163], v[230:233], v[70:73]
	s_setprio 0
	s_setprio 1
	v_mfma_f32_16x16x32_bf16 v[122:125], v[164:167], v[202:205], 0
	v_mfma_f32_16x16x32_bf16 v[114:117], v[172:175], v[202:205], 0
	v_mfma_f32_16x16x32_bf16 v[106:109], v[164:167], v[210:213], 0
	v_mfma_f32_16x16x32_bf16 v[98:101], v[172:175], v[210:213], 0
	v_mfma_f32_16x16x32_bf16 v[90:93], v[164:167], v[218:221], 0
	v_mfma_f32_16x16x32_bf16 v[82:85], v[172:175], v[218:221], 0
	v_mfma_f32_16x16x32_bf16 v[74:77], v[164:167], v[226:229], 0
	v_mfma_f32_16x16x32_bf16 v[66:69], v[172:175], v[226:229], 0
	v_mfma_f32_16x16x32_bf16 v[122:125], v[168:171], v[206:209], v[122:125]
	v_mfma_f32_16x16x32_bf16 v[114:117], v[198:201], v[206:209], v[114:117]
	v_mfma_f32_16x16x32_bf16 v[106:109], v[168:171], v[214:217], v[106:109]
	v_mfma_f32_16x16x32_bf16 v[98:101], v[198:201], v[214:217], v[98:101]
	v_mfma_f32_16x16x32_bf16 v[90:93], v[168:171], v[222:225], v[90:93]
	v_mfma_f32_16x16x32_bf16 v[82:85], v[198:201], v[222:225], v[82:85]
	v_mfma_f32_16x16x32_bf16 v[74:77], v[168:171], v[230:233], v[74:77]
	v_mfma_f32_16x16x32_bf16 v[66:69], v[198:201], v[230:233], v[66:69]
	s_setprio 0
	s_barrier
	s_add_i32 s18, s59, s25
	v_lshl_add_u64 v[176:177], s[6:7], 0, v[134:135]
	s_mov_b32 m0, s18
	ds_read_b128 v[202:205], v197 offset:16384
	ds_read_b128 v[206:209], v197 offset:17408
	ds_read_b128 v[210:213], v197 offset:18432
	ds_read_b128 v[214:217], v197 offset:19456
	ds_read_b128 v[218:221], v197 offset:20480
	ds_read_b128 v[222:225], v197 offset:21504
	ds_read_b128 v[226:229], v197 offset:22528
	ds_read_b128 v[230:233], v197 offset:23552
	global_load_lds_dwordx4 v[176:177], off
	s_add_i32 m0, s18, 0x2000
	s_add_u32 s18, s6, 0x40000
	v_lshl_add_u64 v[234:235], s[6:7], 0, v[130:131]
	s_addc_u32 s19, s7, 0
	s_add_i32 s67, s60, s25
	global_load_lds_dwordx4 v[234:235], off
	v_lshl_add_u64 v[238:239], s[18:19], 0, v[134:135]
	s_mov_b32 m0, s67
	v_lshl_add_u64 v[240:241], s[30:31], 0, v[132:133]
	global_load_lds_dwordx4 v[238:239], off
	v_lshl_add_u64 v[238:239], s[18:19], 0, v[130:131]
	s_add_i32 m0, s67, 0x2000
	s_nop 0
	global_load_lds_dwordx4 v[238:239], off
	v_lshl_add_u64 v[238:239], s[30:31], 0, v[136:137]
	s_mov_b32 m0, s49
	s_nop 0
	global_load_lds_dwordx4 v[238:239], off
	s_mov_b32 m0, s52
	s_nop 0
	global_load_lds_dwordx4 v[240:241], off
	s_waitcnt vmcnt(8)
	s_waitcnt lgkmcnt(0)
	s_barrier
; #define PG8_STAGE(bufoff, gbase, voff) do { _Pragma("unroll") for (int _i = 0; _i < 2; ++_i) \
;         __builtin_amdgcn_global_load_lds((const unsigned*)((const char*)(gbase) + (voff)[_i]), (PG8_LAS unsigned*)(lds + (bufoff) + ldsw + _i * 8192), 16, 0, 0); } while (0)
; #define PG8_LDA(dst, b, h) do { _Pragma("unroll") for (int m = 0; m < 4; ++m) _Pragma("unroll") for (int k = 0; k < 2; ++k) dst[m][k] = *(const PG8_LAS bf16x8*)(lds + PG8_SA(b, h) + aoff + m * 2048 + k * 1024); } while (0)
; #define PG8_LDB(dst, b, h) do { _Pragma("unroll") for (int n = 0; n < 2; ++n) _Pragma("unroll") for (int k = 0; k < 2; ++k) dst[n][k] = *(const PG8_LAS bf16x8*)(lds + PG8_SB(b, h) + boff + n * 2048 + k * 1024); } while (0)
; #define PG8_MMA(ai, bj, At, Bt) do { __builtin_amdgcn_s_setprio(1); _Pragma("unroll") for (int m = 0; m < 4; ++m) _Pragma("unroll") for (int n = 0; n < 2; ++n) _Pragma("unroll") for (int k = 0; k < 2; ++k) \
;         acc[ai][bj][m][n] = __builtin_amdgcn_mfma_f32_16x16x32_bf16(Bt[n][k], At[m][k], acc[ai][bj][m][n], 0, 0, 0); __builtin_amdgcn_s_setprio(0); } while (0)
; #define PG8_WAIT_V(n) asm volatile("s_waitcnt vmcnt(" #n ")" ::: "memory")
; #define PG8_WAIT_L(n) asm volatile("s_waitcnt lgkmcnt(" #n ")" ::: "memory")
; #define PG8_BAR __builtin_amdgcn_s_barrier()
; #define PG8_SCHED __builtin_amdgcn_sched_barrier(0)
; template <class Epi, class Sched, bool ALIGN_EPI = false, bool SP2 = false>
; __device__ __forceinline__ void gemm_phase(PG8_LAS unsigned char* lds, const Gemm g, const Sched& S, const Epi& E) {
;     ...
;             PG8_WAIT_V(8); PG8_WAIT_L(0); PG8_BAR; PG8_MMA(1, 0, At, B0); PG8_MMA(1, 1, At, B1); PG8_BAR; PG8_SCHED;
;             PG8_LDB(B0, 1, 0); PG8_LDB(B1, 1, 1); PG8_SCHED; PG8_LDA(At, 1, 0); PG8_STAGE(PG8_SA(0, 1), a2 + hstep, voffA);
;             PG8_WAIT_V(8); PG8_WAIT_L(0); PG8_BAR; PG8_MMA(0, 0, At, B0); PG8_MMA(0, 1, At, B1); PG8_BAR; PG8_SCHED;
	s_setprio 1
	s_waitcnt lgkmcnt(0)
	v_mfma_f32_16x16x32_bf16 v[62:65], v[148:151], v[202:205], 0
	v_mfma_f32_16x16x32_bf16 v[54:57], v[156:159], v[202:205], 0
	v_mfma_f32_16x16x32_bf16 v[46:49], v[148:151], v[210:213], 0
	v_mfma_f32_16x16x32_bf16 v[38:41], v[156:159], v[210:213], 0
	v_mfma_f32_16x16x32_bf16 v[30:33], v[148:151], v[218:221], 0
	v_mfma_f32_16x16x32_bf16 v[22:25], v[156:159], v[218:221], 0
	v_mfma_f32_16x16x32_bf16 v[14:17], v[148:151], v[226:229], 0
	v_mfma_f32_16x16x32_bf16 v[6:9], v[156:159], v[226:229], 0
	v_mfma_f32_16x16x32_bf16 v[62:65], v[152:155], v[206:209], v[62:65]
	v_mfma_f32_16x16x32_bf16 v[54:57], v[160:163], v[206:209], v[54:57]
	v_mfma_f32_16x16x32_bf16 v[46:49], v[152:155], v[214:217], v[46:49]
	v_mfma_f32_16x16x32_bf16 v[38:41], v[160:163], v[214:217], v[38:41]
	v_mfma_f32_16x16x32_bf16 v[30:33], v[152:155], v[222:225], v[30:33]
	v_mfma_f32_16x16x32_bf16 v[22:25], v[160:163], v[222:225], v[22:25]
	v_mfma_f32_16x16x32_bf16 v[14:17], v[152:155], v[230:233], v[14:17]
	v_mfma_f32_16x16x32_bf16 v[6:9], v[160:163], v[230:233], v[6:9]
	s_setprio 0
	s_setprio 1
	v_mfma_f32_16x16x32_bf16 v[58:61], v[164:167], v[202:205], 0
	v_mfma_f32_16x16x32_bf16 v[50:53], v[172:175], v[202:205], 0
	v_mfma_f32_16x16x32_bf16 v[42:45], v[164:167], v[210:213], 0
	v_mfma_f32_16x16x32_bf16 v[34:37], v[172:175], v[210:213], 0
	v_mfma_f32_16x16x32_bf16 v[26:29], v[164:167], v[218:221], 0
	v_mfma_f32_16x16x32_bf16 v[18:21], v[172:175], v[218:221], 0
	v_mfma_f32_16x16x32_bf16 v[10:13], v[164:167], v[226:229], 0
	v_mfma_f32_16x16x32_bf16 v[2:5], v[172:175], v[226:229], 0
	v_mfma_f32_16x16x32_bf16 v[58:61], v[168:171], v[206:209], v[58:61]
	v_mfma_f32_16x16x32_bf16 v[50:53], v[198:201], v[206:209], v[50:53]
	v_mfma_f32_16x16x32_bf16 v[42:45], v[168:171], v[214:217], v[42:45]
	v_mfma_f32_16x16x32_bf16 v[34:37], v[198:201], v[214:217], v[34:37]
	v_mfma_f32_16x16x32_bf16 v[26:29], v[168:171], v[222:225], v[26:29]
	v_mfma_f32_16x16x32_bf16 v[18:21], v[198:201], v[222:225], v[18:21]
	v_mfma_f32_16x16x32_bf16 v[10:13], v[168:171], v[230:233], v[10:13]
	v_mfma_f32_16x16x32_bf16 v[2:5], v[198:201], v[230:233], v[2:5]
	s_setprio 0
	s_barrier
	s_add_i32 s67, 0, 0x18000
	s_add_i32 s68, 0, 0x1c000
	v_add_u32_e32 v160, s67, v192
	v_add_u32_e32 v198, s68, v192
	ds_read_b128 v[148:151], v160
	ds_read_b128 v[152:155], v160 offset:1024
	ds_read_b128 v[156:159], v160 offset:2048
	ds_read_b128 v[160:163], v160 offset:3072
	ds_read_b128 v[164:167], v198
	ds_read_b128 v[168:171], v198 offset:1024
	ds_read_b128 v[172:175], v198 offset:2048
	ds_read_b128 v[198:201], v198 offset:3072
	s_add_u32 s18, s30, 0x40000
	s_addc_u32 s19, s31, 0
	s_mov_b32 m0, s53
	v_lshl_add_u64 v[242:243], s[18:19], 0, v[136:137]
	ds_read_b128 v[202:205], v197 offset:32768
	ds_read_b128 v[206:209], v197 offset:33792
	ds_read_b128 v[210:213], v197 offset:34816
	ds_read_b128 v[214:217], v197 offset:35840
	ds_read_b128 v[218:221], v197 offset:36864
	ds_read_b128 v[222:225], v197 offset:37888
	ds_read_b128 v[226:229], v197 offset:38912
	ds_read_b128 v[230:233], v197 offset:39936
	global_load_lds_dwordx4 v[242:243], off
	v_lshl_add_u64 v[242:243], s[18:19], 0, v[132:133]
	s_mov_b32 m0, s54
	s_nop 0
	global_load_lds_dwordx4 v[242:243], off
	s_waitcnt vmcnt(8)
	s_waitcnt lgkmcnt(0)
	s_barrier
	s_setprio 1
	s_waitcnt lgkmcnt(0)
	v_mfma_f32_16x16x32_bf16 v[126:129], v[148:151], v[202:205], v[126:129]
	v_mfma_f32_16x16x32_bf16 v[118:121], v[156:159], v[202:205], v[118:121]
	v_mfma_f32_16x16x32_bf16 v[110:113], v[148:151], v[210:213], v[110:113]
	v_mfma_f32_16x16x32_bf16 v[102:105], v[156:159], v[210:213], v[102:105]
	v_mfma_f32_16x16x32_bf16 v[94:97], v[148:151], v[218:221], v[94:97]
	v_mfma_f32_16x16x32_bf16 v[86:89], v[156:159], v[218:221], v[86:89]
	v_mfma_f32_16x16x32_bf16 v[78:81], v[148:151], v[226:229], v[78:81]
	v_mfma_f32_16x16x32_bf16 v[70:73], v[156:159], v[226:229], v[70:73]
	v_mfma_f32_16x16x32_bf16 v[126:129], v[152:155], v[206:209], v[126:129]
	v_mfma_f32_16x16x32_bf16 v[118:121], v[160:163], v[206:209], v[118:121]
	v_mfma_f32_16x16x32_bf16 v[110:113], v[152:155], v[214:217], v[110:113]
	v_mfma_f32_16x16x32_bf16 v[102:105], v[160:163], v[214:217], v[102:105]
	v_mfma_f32_16x16x32_bf16 v[94:97], v[152:155], v[222:225], v[94:97]
	v_mfma_f32_16x16x32_bf16 v[86:89], v[160:163], v[222:225], v[86:89]
	v_mfma_f32_16x16x32_bf16 v[78:81], v[152:155], v[230:233], v[78:81]
	v_mfma_f32_16x16x32_bf16 v[70:73], v[160:163], v[230:233], v[70:73]
	s_setprio 0
	s_setprio 1
	v_mfma_f32_16x16x32_bf16 v[122:125], v[164:167], v[202:205], v[122:125]
	v_mfma_f32_16x16x32_bf16 v[114:117], v[172:175], v[202:205], v[114:117]
	v_mfma_f32_16x16x32_bf16 v[106:109], v[164:167], v[210:213], v[106:109]
	v_mfma_f32_16x16x32_bf16 v[98:101], v[172:175], v[210:213], v[98:101]
	v_mfma_f32_16x16x32_bf16 v[90:93], v[164:167], v[218:221], v[90:93]
	v_mfma_f32_16x16x32_bf16 v[82:85], v[172:175], v[218:221], v[82:85]
	v_mfma_f32_16x16x32_bf16 v[74:77], v[164:167], v[226:229], v[74:77]
	v_mfma_f32_16x16x32_bf16 v[66:69], v[172:175], v[226:229], v[66:69]
	v_mfma_f32_16x16x32_bf16 v[122:125], v[168:171], v[206:209], v[122:125]
	v_mfma_f32_16x16x32_bf16 v[114:117], v[198:201], v[206:209], v[114:117]
	v_mfma_f32_16x16x32_bf16 v[106:109], v[168:171], v[214:217], v[106:109]
	v_mfma_f32_16x16x32_bf16 v[98:101], v[198:201], v[214:217], v[98:101]
	v_mfma_f32_16x16x32_bf16 v[90:93], v[168:171], v[222:225], v[90:93]
	v_mfma_f32_16x16x32_bf16 v[82:85], v[198:201], v[222:225], v[82:85]
	v_mfma_f32_16x16x32_bf16 v[74:77], v[168:171], v[230:233], v[74:77]
	v_mfma_f32_16x16x32_bf16 v[66:69], v[198:201], v[230:233], v[66:69]
	s_setprio 0
	s_barrier
; #define PG8_STAGE(bufoff, gbase, voff) do { _Pragma("unroll") for (int _i = 0; _i < 2; ++_i) \
;         __builtin_amdgcn_global_load_lds((const unsigned*)((const char*)(gbase) + (voff)[_i]), (PG8_LAS unsigned*)(lds + (bufoff) + ldsw + _i * 8192), 16, 0, 0); } while (0)
; #define PG8_LDA(dst, b, h) do { _Pragma("unroll") for (int m = 0; m < 4; ++m) _Pragma("unroll") for (int k = 0; k < 2; ++k) dst[m][k] = *(const PG8_LAS bf16x8*)(lds + PG8_SA(b, h) + aoff + m * 2048 + k * 1024); } while (0)
; #define PG8_MMA(ai, bj, At, Bt) do { __builtin_amdgcn_s_setprio(1); _Pragma("unroll") for (int m = 0; m < 4; ++m) _Pragma("unroll") for (int n = 0; n < 2; ++n) _Pragma("unroll") for (int k = 0; k < 2; ++k) \
;         acc[ai][bj][m][n] = __builtin_amdgcn_mfma_f32_16x16x32_bf16(Bt[n][k], At[m][k], acc[ai][bj][m][n], 0, 0, 0); __builtin_amdgcn_s_setprio(0); } while (0)
; #define PG8_WAIT_V(n) asm volatile("s_waitcnt vmcnt(" #n ")" ::: "memory")
; #define PG8_WAIT_L(n) asm volatile("s_waitcnt lgkmcnt(" #n ")" ::: "memory")
; #define PG8_BAR __builtin_amdgcn_s_barrier()
; #define PG8_SCHED __builtin_amdgcn_sched_barrier(0)
; template <class Epi, class Sched, bool ALIGN_EPI = false, bool SP2 = false>
; __device__ __forceinline__ void gemm_phase(PG8_LAS unsigned char* lds, const Gemm g, const Sched& S, const Epi& E) {
;     ...
;         for (int t = 0; t < nt; t += 2) {
;     ...
;             PG8_WAIT_V(8); PG8_WAIT_L(0); PG8_BAR; PG8_MMA(0, 0, At, B0); PG8_MMA(0, 1, At, B1); PG8_BAR; PG8_SCHED;
;             PG8_LDA(At, 1, 1); PG8_STAGE(PG8_SB(1, 0), b3, voffB); PG8_STAGE(PG8_SB(1, 1), b3 + hstep, voffB); PG8_STAGE(PG8_SA(1, 0), a3, voffA);
;             PG8_WAIT_V(8); PG8_WAIT_L(0); PG8_BAR; PG8_MMA(1, 0, At, B0); PG8_MMA(1, 1, At, B1); PG8_BAR; PG8_SCHED;
	s_add_i32 s18, s67, s25
	v_lshl_add_u64 v[176:177], v[176:177], 0, s[14:15]
	s_mov_b32 m0, s18
	ds_read_b128 v[202:205], v197 offset:49152
	ds_read_b128 v[206:209], v197 offset:50176
	ds_read_b128 v[210:213], v197 offset:51200
	ds_read_b128 v[214:217], v197 offset:52224
	ds_read_b128 v[218:221], v197 offset:53248
	ds_read_b128 v[222:225], v197 offset:54272
	ds_read_b128 v[226:229], v197 offset:55296
	ds_read_b128 v[230:233], v197 offset:56320
	global_load_lds_dwordx4 v[176:177], off
	s_add_i32 m0, s18, 0x2000
	s_add_u32 s6, s6, 0x40080
	v_lshl_add_u64 v[176:177], v[234:235], 0, s[14:15]
	s_addc_u32 s7, s7, 0
	s_add_i32 s18, s68, s25
	global_load_lds_dwordx4 v[176:177], off
	v_lshl_add_u64 v[176:177], s[6:7], 0, v[134:135]
	s_mov_b32 m0, s18
	s_nop 0
	global_load_lds_dwordx4 v[176:177], off
	v_lshl_add_u64 v[176:177], s[6:7], 0, v[130:131]
	s_add_i32 m0, s18, 0x2000
	s_nop 0
	global_load_lds_dwordx4 v[176:177], off
	v_lshl_add_u64 v[176:177], v[238:239], 0, s[14:15]
	s_mov_b32 m0, s56
	s_nop 0
	global_load_lds_dwordx4 v[176:177], off
	v_lshl_add_u64 v[176:177], v[240:241], 0, s[14:15]
	s_mov_b32 m0, s57
	s_nop 0
	global_load_lds_dwordx4 v[176:177], off
	s_waitcnt vmcnt(8)
	s_waitcnt lgkmcnt(0)
	s_barrier
	s_setprio 1
	s_waitcnt lgkmcnt(0)
	v_mfma_f32_16x16x32_bf16 v[62:65], v[148:151], v[202:205], v[62:65]
	v_mfma_f32_16x16x32_bf16 v[54:57], v[156:159], v[202:205], v[54:57]
	v_mfma_f32_16x16x32_bf16 v[46:49], v[148:151], v[210:213], v[46:49]
	v_mfma_f32_16x16x32_bf16 v[38:41], v[156:159], v[210:213], v[38:41]
	v_mfma_f32_16x16x32_bf16 v[30:33], v[148:151], v[218:221], v[30:33]
	v_mfma_f32_16x16x32_bf16 v[22:25], v[156:159], v[218:221], v[22:25]
	v_mfma_f32_16x16x32_bf16 v[14:17], v[148:151], v[226:229], v[14:17]
	v_mfma_f32_16x16x32_bf16 v[6:9], v[156:159], v[226:229], v[6:9]
	v_mfma_f32_16x16x32_bf16 v[62:65], v[152:155], v[206:209], v[62:65]
	v_mfma_f32_16x16x32_bf16 v[54:57], v[160:163], v[206:209], v[54:57]
	v_mfma_f32_16x16x32_bf16 v[46:49], v[152:155], v[214:217], v[46:49]
	v_mfma_f32_16x16x32_bf16 v[38:41], v[160:163], v[214:217], v[38:41]
	v_mfma_f32_16x16x32_bf16 v[30:33], v[152:155], v[222:225], v[30:33]
	v_mfma_f32_16x16x32_bf16 v[22:25], v[160:163], v[222:225], v[22:25]
	v_mfma_f32_16x16x32_bf16 v[14:17], v[152:155], v[230:233], v[14:17]
	v_mfma_f32_16x16x32_bf16 v[6:9], v[160:163], v[230:233], v[6:9]
	s_setprio 0
	s_setprio 1
	v_mfma_f32_16x16x32_bf16 v[58:61], v[164:167], v[202:205], v[58:61]
	v_mfma_f32_16x16x32_bf16 v[50:53], v[172:175], v[202:205], v[50:53]
	v_mfma_f32_16x16x32_bf16 v[42:45], v[164:167], v[210:213], v[42:45]
	v_mfma_f32_16x16x32_bf16 v[34:37], v[172:175], v[210:213], v[34:37]
	v_mfma_f32_16x16x32_bf16 v[26:29], v[164:167], v[218:221], v[26:29]
	v_mfma_f32_16x16x32_bf16 v[18:21], v[172:175], v[218:221], v[18:21]
	v_mfma_f32_16x16x32_bf16 v[10:13], v[164:167], v[226:229], v[10:13]
	v_mfma_f32_16x16x32_bf16 v[2:5], v[172:175], v[226:229], v[2:5]
	v_mfma_f32_16x16x32_bf16 v[58:61], v[168:171], v[206:209], v[58:61]
	v_mfma_f32_16x16x32_bf16 v[50:53], v[198:201], v[206:209], v[50:53]
	v_mfma_f32_16x16x32_bf16 v[42:45], v[168:171], v[214:217], v[42:45]
	v_mfma_f32_16x16x32_bf16 v[34:37], v[198:201], v[214:217], v[34:37]
	v_mfma_f32_16x16x32_bf16 v[26:29], v[168:171], v[222:225], v[26:29]
	v_mfma_f32_16x16x32_bf16 v[18:21], v[198:201], v[222:225], v[18:21]
	v_mfma_f32_16x16x32_bf16 v[10:13], v[168:171], v[230:233], v[10:13]
	v_mfma_f32_16x16x32_bf16 v[2:5], v[198:201], v[230:233], v[2:5]
	s_setprio 0
	s_barrier
	s_add_i32 s66, s66, 2
	s_add_u32 s4, s4, 0x100
	s_addc_u32 s5, s5, 0
	s_add_u32 s46, s46, 0x100
	s_addc_u32 s47, s47, 0
	s_cmp_gt_u32 s66, 13
	s_cbranch_scc1 .Lpeel_done_738

; #define PG8_BAR __builtin_amdgcn_s_barrier()
; template <class Epi, class Sched, bool ALIGN_EPI = false, bool SP2 = false>
; __device__ __forceinline__ void gemm_phase(PG8_LAS unsigned char* lds, const Gemm g, const Sched& S, const Epi& E) {
;     ...
;         if constexpr (ALIGN_EPI) { if (wr == 0) PG8_BAR; }
.Lpeel_done_738:
	s_and_b64 vcc, exec, s[16:17]
	s_cbranch_vccz .LBB0_741
	s_barrier
